# phase loop: no grid barrier in front of the empty last phase (the final norm is fused into the last down-GEMM epilogue when there are 256 workgroups)
# speedup vs baseline: 1.0015x; 1.0015x over previous
; #define LAS __attribute__((address_space(3)))
; __device__ __forceinline__ unsigned xb_xcc_id() { return (unsigned)__builtin_amdgcn_s_getreg((3 << 11) | 20) & 0xFu; }
; __global__ void __launch_bounds__(NTHREADS, 2) mega_fwd(Args A_unused) {
;     ...
;         const bool flag_seam = (PROBE_PH < 0) && ph >= 1 && ph <= 12 && ((ph - 1) % 6) == 1;
;         if (st + 1 < st_hi && !flag_seam) {
;             if (ph_hi > 100000) grid.sync();
;             XcdBarrier xb; xb.bar = (unsigned*)(ws + WS_CTL); xb.x = xb_xcc_id(); xb.st = (volatile LAS unsigned*)(lds + LDS_BAR_OFF);
;             xcd_barrier(xb, tid);
;         }
.LBB0_847:
	s_add_i32 s2, s64, -1
	s_cmp_lt_u32 s2, 12
	s_cselect_b64 s[0:1], -1, 0
	s_add_i32 s3, s64, -7
	s_cmp_lt_u32 s2, 6
	s_cselect_b32 s2, s2, s3
	s_cmp_eq_u32 s2, 1
	s_cselect_b64 s[2:3], -1, 0
	s_and_b64 s[0:1], s[0:1], s[2:3]
	s_add_i32 s64, s64, 1
	s_cmp_eq_u32 s97, 0x100
	s_cselect_b32 s2, 13, s65
	s_min_i32 s2, s2, s65
	s_cmp_ge_i32 s64, s2
	s_cselect_b64 s[2:3], -1, 0
	s_or_b64 s[0:1], s[2:3], s[0:1]
	s_and_b64 vcc, exec, s[0:1]
	s_cbranch_vccz .LBB0_848
	s_getpc_b64 s[98:99]
